# bundle25 + one static s_setprio 1 for waves 4-7 across the forgetting-attention loop (lever 4), reset at the phase exit
# speedup vs baseline: 1.0057x; 1.0057x over previous
.LBB0_1132:
	s_or_b64 exec, exec, s[0:1]
	s_cmpk_lt_i32 s84, 0x100
	s_cselect_b64 s[34:35], -1, 0
	s_cmpk_gt_i32 s84, 0xff
	s_waitcnt vmcnt(0) lgkmcnt(0)
	s_barrier
	s_cbranch_scc1 .LBB0_1246
	v_readfirstlane_b32 s0, v0
	s_nop 3
	s_and_b32 s0, s0, 0x3ff
	s_lshr_b32 s0, s0, 6
	s_cmp_ge_u32 s0, 4
	s_cbranch_scc0 .Lattn_prio_done
	s_setprio 1
.Lattn_prio_done:
	s_add_u32 s18, s26, 0x15c00000
	s_addc_u32 s19, s27, 0
	s_add_u32 s22, s26, 0x19c00000
	s_addc_u32 s23, s27, 0
	s_add_u32 s28, s26, 0x1dc00000
	s_addc_u32 s29, s27, 0
	v_lshrrev_b32_e32 v5, 5, v252
	s_cmp_lg_u32 0, -1
	v_lshlrev_b32_e32 v1, 1, v0
	s_cselect_b32 s0, 0, 0
	v_lshlrev_b32_e32 v223, 2, v5
	v_lshrrev_b32_e32 v8, 2, v0
	v_lshlrev_b32_e32 v7, 3, v0
	v_and_b32_e32 v1, 32, v1
	s_addk_i32 s0, 0x6000
	v_and_or_b32 v8, v8, 3, v223
	v_and_b32_e32 v222, 31, v0
	v_and_b32_e32 v4, 24, v7
	v_add_u32_e32 v6, s0, v1
	v_lshlrev_b32_e32 v8, 6, v8
	v_add_u32_e32 v1, 0, v1
	v_add3_u32 v224, v6, v4, v8
	v_lshlrev_b32_e32 v6, 10, v5
	v_lshlrev_b32_e32 v9, 4, v222
	v_add3_u32 v226, v1, v4, v8
	v_lshlrev_b32_e32 v1, 10, v222
	v_add3_u32 v225, 0, v6, v9
	v_lshl_or_b32 v6, v5, 3, v1
	v_lshlrev_b32_e32 v9, 4, v5
	v_lshlrev_b32_e32 v241, 9, v5
	v_lshrrev_b32_e32 v5, 3, v252
	s_add_i32 s0, 0, 0x14800
	v_and_b32_e32 v8, 56, v7
	v_or_b32_e32 v7, 8, v5
	v_lshlrev_b32_e32 v3, 4, v0
	v_lshlrev_b32_e32 v2, 10, v252
	v_mov_b32_e32 v195, 0
	v_add_u32_e32 v227, s0, v9
	s_add_i32 s0, 0, 0x14900
	v_lshlrev_b32_e32 v242, 7, v5
	v_lshlrev_b32_e32 v10, 11, v5
	v_lshlrev_b32_e32 v243, 7, v7
	v_lshlrev_b32_e32 v12, 11, v7
	v_or_b32_e32 v7, 16, v5
	v_or_b32_e32 v5, 24, v5
	v_lshlrev_b32_e32 v194, 8, v0
	v_add_u32_e32 v228, s0, v9
	v_lshlrev_b32_e32 v14, 11, v7
	v_lshlrev_b32_e32 v245, 7, v5
	v_lshlrev_b32_e32 v16, 11, v5
	v_lshl_add_u64 v[18:19], s[26:27], 0, v[194:195]
	s_mov_b64 s[0:1], 0x11800000
	v_add_u32_e32 v5, 0, v9
	v_add_u32_e32 v3, 0, v3
	v_lshlrev_b32_e32 v194, 1, v2
	s_mov_b32 s52, 0xfffe0000
	v_mbcnt_lo_u32_b32 v2, -1, 0
	s_mov_b32 s37, 0
	v_cmp_eq_u32_e64 s[2:3], 0, v252
	v_cmp_gt_u32_e64 s[4:5], 2, v252
	v_cmp_gt_u32_e64 s[6:7], 4, v252
	v_cmp_gt_u32_e64 s[8:9], 8, v252
	v_cmp_gt_u32_e64 s[10:11], 16, v252
	v_cmp_eq_u32_e64 s[12:13], 63, v252
	v_cmp_gt_u32_e64 s[14:15], 32, v252
	s_mov_b32 s61, -1
	v_or_b32_e32 v229, 0xc0, v223
	v_or_b32_e32 v1, 0xf2, v223
	v_or_b32_e32 v247, 0xd3, v223
	v_or_b32_e32 v232, 0xf3, v223
	v_or_b32_e32 v233, 0xd8, v223
	v_or_b32_e32 v234, 0xf8, v223
	v_or_b32_e32 v235, 0xd9, v223
	v_or_b32_e32 v236, 0xf9, v223
	v_or_b32_e32 v237, 0xda, v223
	v_or_b32_e32 v238, 0xfa, v223
	v_or_b32_e32 v239, 0xdb, v223
	v_or_b32_e32 v240, 0xfb, v223
	s_mov_b32 s31, 7
	v_lshlrev_b32_e32 v244, 7, v7
	v_lshl_add_u64 v[196:197], v[18:19], 0, s[0:1]
	v_add_u32_e32 v246, 0x14a00, v5
	s_mov_b32 s40, 0xbfb8aa3b
	v_add_u32_e32 v248, 0x14800, v3
	v_lshlrev_b32_e32 v198, 1, v4
	s_mov_b64 s[42:43], 0x20000
	v_lshlrev_b32_e32 v249, 1, v6
	s_mov_b64 s[44:45], 0x40000
	s_mov_b64 s[46:47], 0x60000
	s_mov_b64 s[48:49], 0xa0000
	s_mov_b32 s53, -1
	s_mov_b32 s41, 0x42200000
	s_mov_b64 s[54:55], 0x80000
	v_lshlrev_b32_e32 v200, 1, v8
	v_lshlrev_b32_e32 v202, 1, v10
	v_lshlrev_b32_e32 v204, 1, v12
	v_lshlrev_b32_e32 v206, 1, v14
	v_lshlrev_b32_e32 v208, 1, v16
	v_mbcnt_hi_u32_b32 v250, -1, v2
	v_mov_b32_e32 v251, 0xff800000
	s_mov_b32 s66, 0
	s_mov_b32 s68, s84
	s_mov_b32 s60, 7
	s_branch .LBB0_1135

.LBB0_1246:
	s_setprio 0
	s_andn2_b64 vcc, exec, s[34:35]
	s_barrier
	s_cbranch_vccnz .LBB0_1253
	s_add_u32 s12, s26, 0x11000000
	s_addc_u32 s13, s27, 0
	s_add_u32 s2, s26, 0x11400000
	v_mbcnt_lo_u32_b32 v1, -1, 0
	s_addc_u32 s3, s27, 0
	v_mbcnt_hi_u32_b32 v148, -1, v1
	s_add_u32 s4, s26, 0x21c00000
	v_and_b32_e32 v1, 64, v148
	s_addc_u32 s5, s27, 0
	s_lshl_b32 s14, s84, 9
	s_lshl_b32 s15, s84, 5
	s_lshl_b32 s16, s33, 5
	s_mov_b32 s7, 0
	v_mov_b32_e32 v147, 0
	s_mov_b32 s17, 0x8000
	s_mov_b32 s18, 0x10000
	s_mov_b32 s19, 0x18000
	s_mov_b32 s22, 0x20000
	s_mov_b32 s23, 0x28000
	s_mov_b32 s28, 0x30000
	s_mov_b32 s29, 0x38000
	v_xor_b32_e32 v149, 1, v148
	v_add_u32_e32 v150, 64, v1
	v_xor_b32_e32 v151, 2, v148
	v_xor_b32_e32 v152, 4, v148
	v_xor_b32_e32 v153, 8, v148
	v_mov_b32_e32 v154, 0x358637bd
	s_mov_b32 s31, 0xf800000
	v_mov_b32_e32 v155, 0x260
	s_movk_i32 s34, 0x110
	s_add_i32 s35, 0, 0x11000
	s_movk_i32 s36, 0x208
	s_mov_b32 s37, 0x40000
	s_mov_b32 s40, 0x60000
	s_mov_b32 s41, 0x80000
	s_mov_b32 s42, 0xa0000
	s_mov_b32 s43, 0xc0000
	s_mov_b32 s44, 0xe0000
	v_xor_b32_e32 v156, 32, v148
	s_branch .LBB0_1249
